# hyena: each block prefetches a 32KB slice of the filter-MLP activations into its XCD L2 at channel start
# baseline (speedup 1.0000x reference)
; __device__ __forceinline__ void phase_hyena(KP kp_, int hf){ asm volatile("" : "+s"(kp_)); const Params p=load_params(kp_);
;     ...
;   for (int cl=blockIdx.x; cl<512; cl+=gridDim.x){ int c=hf*512+cl;
;     asm volatile("" : "+v"(tid)); lane=tid&63; wid=tid>>6;
;     __syncthreads();
;     if (tid<256){ int i=tid>>2, so=tid&3; misc[tid]=p.f_wout[(size_t)i*4096+(so>>1)*2048+(so&1)*1024+c]; }
.LBB0_1193:
	v_readlane_b32 s10, v253, 2
	s_add_i32 s10, s90, s10
	s_movk_i32 s11, 0xff
	s_waitcnt lgkmcnt(0)
	v_cmp_lt_i32_e32 vcc, s11, v86
	s_barrier
	v_readlane_b32 s98, v253, 6
	v_lshlrev_b32_e32 v232, 4, v154
	s_nop 1
	s_lshr_b32 s98, s98, 3
	s_and_b32 s98, s98, 31
	s_lshl_b32 s98, s98, 15
	s_add_u32 s98, s98, 0x3b89000
	v_add_u32_e32 v232, s98, v232
	v_add_u32_e32 v233, 0x2000, v232
	v_add_u32_e32 v234, 0x4000, v232
	v_add_u32_e32 v235, 0x6000, v232
	global_load_dwordx4 v[228:231], v232, s[70:71]
	global_load_dwordx4 v[228:231], v233, s[70:71]
	global_load_dwordx4 v[228:231], v234, s[70:71]
	global_load_dwordx4 v[228:231], v235, s[70:71]
	s_and_saveexec_b64 s[12:13], vcc
	s_xor_b64 s[12:13], exec, s[12:13]
	s_ashr_i32 s11, s10, 31
	s_or_saveexec_b64 s[12:13], s[12:13]
	v_mov_b64_e32 v[0:1], s[10:11]
	s_xor_b64 exec, exec, s[12:13]
	s_cbranch_execz .LBB0_1197
	v_ashrrev_i32_e32 v0, 2, v86
	v_ashrrev_i32_e32 v1, 31, v0
	v_readlane_b32 s14, v252, 10
	v_lshlrev_b64 v[0:1], 14, v[0:1]
	v_readlane_b32 s15, v252, 11
	v_lshlrev_b32_e32 v2, 12, v86
	v_and_b32_e32 v132, 0x2000, v2
	v_lshl_add_u64 v[0:1], s[14:15], 0, v[0:1]
	v_lshl_add_u64 v[0:1], v[0:1], 0, v[132:133]
	v_and_b32_e32 v132, 0x1000, v2
	s_ashr_i32 s11, s10, 31
	v_lshl_add_u64 v[0:1], v[0:1], 0, v[132:133]
	v_lshl_add_u64 v[0:1], s[10:11], 2, v[0:1]
	flat_load_dword v0, v[0:1]
	v_lshl_add_u32 v1, v86, 2, 0
	v_add_u32_e32 v1, 0x20000, v1
	s_waitcnt vmcnt(0) lgkmcnt(0)
	ds_write_b32 v1, v0
	v_mov_b64_e32 v[0:1], s[10:11]
